# S unit: queue index popped one unit ahead (atomic latency hidden), gate value loaded at merge start
# speedup vs baseline: 1.0173x; 1.0003x over previous
; DI float fexp2(float x) { return __builtin_amdgcn_exp2f(x); }
; DI void unit_sample_attn2(int u, const bf16* __restrict__ Q, const float* __restrict__ ckw, const float* __restrict__ cvw, const float* __restrict__ nkw, const float* __restrict__ nvw, const bf16* __restrict__ G, bf16* __restrict__ MIX, ...
;     ...
;     {   const int jj = tid >> 7, e = tid & 127, h2 = e >> 6;
;         float M = NEG;
; #pragma unroll
;         for (int w2 = 0; w2 < 4; ++w2) { const int w = (jj + 4 * (w2 >> 1)) * 2 + (w2 & 1); M = fmaxf(M, sB[w * 2 + h2]); }
; #pragma unroll
;         for (int w = 0; w < 16; ++w) M = fmaxf(M, sA[(w * 4 + jj) * 2 + h2]);
;         float num = 0.f, den = 0.f;
; #pragma unroll
;         for (int w = 0; w < 16; ++w) { const float f = fexp2(sA[(w * 4 + jj) * 2 + h2] - M); num += f * pA[(w * 4 + jj) * 128 + e]; den += f * sA[128 + (w * 4 + jj) * 2 + h2]; }
.Lsq_entry:
	s_and_saveexec_b64 s[0:1], s[56:57]
	v_mov_b32_e32 v227, 1
	global_atomic_add v227, v2, v227, s[58:59] sc0
	s_mov_b64 exec, s[0:1]
	s_branch .LBB0_722
.LBB0_720:
	s_or_b64 exec, exec, s[2:3]
	v_ashrrev_i32_e32 v14, 7, v3
	v_and_b32_e32 v13, 0x7f, v3
	v_add_u32_e32 v242, s34, v14
	v_or_b32_e32 v244, s38, v13
	v_ashrrev_i32_e32 v243, 31, v242
	v_add_u32_e32 v244, 0x100, v244
	v_lshlrev_b64 v[242:243], 11, v[242:243]
	s_nop 0
	v_lshl_or_b32 v242, v244, 1, v242
	v_lshl_add_u64 v[244:245], s[24:25], 0, v[242:243]
	global_load_ushort v244, v[244:245], off
	v_lshrrev_b32_e32 v3, 4, v3
	v_lshlrev_b32_e32 v4, 4, v14
	v_and_b32_e32 v3, 4, v3
	v_add3_u32 v16, 0, v4, v3
	v_add_u32_e32 v4, 0xa400, v16
	s_waitcnt lgkmcnt(0)
	s_barrier
	ds_read2_b32 v[6:7], v4 offset1:2
	s_addk_i32 s38, 0x100
	s_mov_b64 s[2:3], 0
	s_waitcnt lgkmcnt(0)
	v_max3_f32 v8, v6, s45, v7
	v_add_u32_e32 v7, 4, v14
	v_lshlrev_b32_e32 v4, 4, v7
	v_add3_u32 v15, 0, v4, v3
	v_add_u32_e32 v4, 0xa400, v15
	ds_read2_b32 v[4:5], v4 offset1:2
	s_waitcnt lgkmcnt(0)
	v_max3_f32 v5, v8, v4, v5
	v_lshlrev_b32_e32 v8, 3, v14
	v_sub_u32_e32 v12, v16, v8
	v_add_u32_e32 v17, 0xa000, v12
	ds_read2_b32 v[8:9], v17 offset1:8
	ds_read2_b32 v[10:11], v17 offset0:16 offset1:24
	ds_read2_b32 v[18:19], v17 offset0:32 offset1:40
	ds_read2_b32 v[20:21], v17 offset0:48 offset1:56
	s_waitcnt lgkmcnt(3)
	v_max3_f32 v5, v5, v8, v9
	s_waitcnt lgkmcnt(2)
	v_max3_f32 v5, v5, v10, v11
	s_waitcnt lgkmcnt(1)
	v_max3_f32 v5, v5, v18, v19
	s_waitcnt lgkmcnt(0)
	v_max3_f32 v5, v5, v20, v21
	ds_read2_b32 v[20:21], v17 offset0:64 offset1:72
	s_waitcnt lgkmcnt(0)
	v_max3_f32 v5, v5, v20, v21
	ds_read2_b32 v[20:21], v17 offset0:80 offset1:88
	s_waitcnt lgkmcnt(0)
	v_max3_f32 v5, v5, v20, v21
	ds_read2_b32 v[20:21], v17 offset0:96 offset1:104
	s_waitcnt lgkmcnt(0)
	v_max3_f32 v5, v5, v20, v21
	ds_read2_b32 v[20:21], v17 offset0:112 offset1:120
	s_waitcnt lgkmcnt(0)
	v_max3_f32 v17, v5, v20, v21
	v_lshl_add_u32 v5, v13, 2, 0
	v_lshl_add_u32 v19, v14, 9, v5
	v_sub_f32_e32 v9, v9, v17
	ds_read_b32 v20, v19
	ds_read_b32 v21, v12 offset:41472
	v_lshlrev_b32_e32 v19, 3, v7
	v_exp_f32_e32 v12, v9
	v_lshl_add_u32 v9, v7, 9, v5
	ds_read_b32 v22, v9
	v_sub_u32_e32 v9, v15, v19
	ds_read_b32 v23, v9 offset:41472
	v_add_u32_e32 v9, 8, v14
	v_lshlrev_b32_e32 v19, 3, v9
	v_lshl_add_u32 v9, v9, 9, v5
	ds_read_b32 v24, v9
	v_add3_u32 v9, 0, v19, v3
	ds_read_b32 v25, v9 offset:41472
	v_add_u32_e32 v9, 12, v14
	v_lshlrev_b32_e32 v19, 3, v9
	v_lshl_add_u32 v9, v9, 9, v5
	ds_read_b32 v28, v9
	v_add3_u32 v9, 0, v19, v3
	v_sub_f32_e32 v11, v11, v17
	ds_read_b32 v29, v9 offset:41472
	v_add_u32_e32 v9, 16, v14
	v_exp_f32_e32 v26, v11
	v_lshlrev_b32_e32 v11, 3, v9
	v_lshl_add_u32 v9, v9, 9, v5
	ds_read_b32 v30, v9
	v_add3_u32 v9, 0, v11, v3
	ds_read_b32 v31, v9 offset:41472
	v_add_u32_e32 v9, 20, v14
	v_lshlrev_b32_e32 v11, 3, v9
	v_add3_u32 v11, 0, v11, v3
	ds_read2st64_b32 v[32:33], v11 offset0:160 offset1:162
	v_lshl_add_u32 v9, v9, 9, v5
	v_sub_f32_e32 v8, v8, v17
	v_exp_f32_e32 v8, v8
	v_sub_f32_e32 v10, v10, v17
	s_waitcnt lgkmcnt(0)
	v_sub_f32_e32 v11, v32, v17
	ds_read_b32 v32, v9
	v_add_u32_e32 v9, 24, v14
	v_exp_f32_e32 v34, v11
	v_lshlrev_b32_e32 v11, 3, v9
	v_add3_u32 v11, 0, v11, v3
	ds_read2st64_b32 v[36:37], v11 offset0:160 offset1:162
	v_lshl_add_u32 v9, v9, 9, v5
	v_exp_f32_e32 v10, v10
	v_sub_f32_e32 v18, v18, v17
	v_exp_f32_e32 v18, v18
	s_waitcnt lgkmcnt(0)
	v_sub_f32_e32 v11, v36, v17
	ds_read_b32 v36, v9
	v_add_u32_e32 v9, 28, v14
	v_exp_f32_e32 v38, v11
	v_lshlrev_b32_e32 v11, 3, v9
	v_add3_u32 v11, 0, v11, v3
	ds_read2st64_b32 v[40:41], v11 offset0:160 offset1:162
	v_lshl_add_u32 v9, v9, 9, v5
	v_sub_f32_e32 v6, v6, v17
	v_exp_f32_e32 v6, v6
	v_sub_f32_e32 v4, v4, v17
	s_waitcnt lgkmcnt(0)
	v_sub_f32_e32 v11, v40, v17
	ds_read_b32 v40, v9
	v_pk_fma_f32 v[8:9], v[20:21], v[8:9], 0 op_sel_hi:[1,0,0]
	v_exp_f32_e32 v42, v11
	v_pk_fma_f32 v[8:9], v[22:23], v[12:13], v[8:9] op_sel_hi:[1,0,1]
	v_add_u32_e32 v21, 36, v14
	v_pk_fma_f32 v[8:9], v[24:25], v[10:11], v[8:9] op_sel_hi:[1,0,1]
	v_exp_f32_e32 v4, v4
	v_pk_fma_f32 v[8:9], v[28:29], v[26:27], v[8:9] op_sel_hi:[1,0,1]
	s_nop 0
	v_pk_fma_f32 v[8:9], v[30:31], v[18:19], v[8:9] op_sel_hi:[1,0,1]
	v_add_u32_e32 v18, 32, v14
	v_lshlrev_b32_e32 v10, 3, v18
	v_add3_u32 v10, 0, v10, v3
	ds_read2st64_b32 v[10:11], v10 offset0:160 offset1:162
	v_pk_fma_f32 v[8:9], v[32:33], v[34:35], v[8:9] op_sel_hi:[1,0,1]
	s_waitcnt lgkmcnt(0)
; DI unsigned cvtpk(float lo, float hi) { f32x2_t v = {lo, hi}; bf16x2_t b = __builtin_convertvector(v, bf16x2_t); return __builtin_bit_cast(unsigned, b); }
; DI float fexp2(float x) { return __builtin_amdgcn_exp2f(x); }
; DI void unit_sample_attn2(int u, const bf16* __restrict__ Q, const float* __restrict__ ckw, const float* __restrict__ cvw, const float* __restrict__ nkw, const float* __restrict__ nvw, const bf16* __restrict__ G, bf16* __restrict__ MIX, ...
;     ...
;         float num = 0.f, den = 0.f;
; #pragma unroll
;         for (int w = 0; w < 16; ++w) { const float f = fexp2(sA[(w * 4 + jj) * 2 + h2] - M); num += f * pA[(w * 4 + jj) * 128 + e]; den += f * sA[128 + (w * 4 + jj) * 2 + h2]; }
; #pragma unroll
;         for (int w2 = 0; w2 < 4; ++w2) { const int w = (jj + 4 * (w2 >> 1)) * 2 + (w2 & 1); const float f = fexp2(sB[w * 2 + h2] - M); num += f * pB[w * 128 + e]; den += f * sB[32 + w * 2 + h2]; }
;         const size_t srow = (size_t)(MP + b * 4 + jj); const int col = 256 + hq * 128 + e;
;         const float g = bflo((unsigned)G[srow * D + col]);
;         MIX[srow * D + col] = (bf16)(cvtpk(num / den * g, 0.f) & 0xffffu); }
	v_sub_f32_e32 v10, v10, v17
	v_exp_f32_e32 v12, v10
	v_lshl_add_u32 v10, v18, 9, v5
	v_lshlrev_b32_e32 v18, 3, v21
	v_add3_u32 v18, 0, v18, v3
	ds_read2st64_b32 v[18:19], v18 offset0:160 offset1:162
	ds_read_b32 v10, v10
	v_pk_fma_f32 v[8:9], v[36:37], v[38:39], v[8:9] op_sel_hi:[1,0,1]
	s_waitcnt lgkmcnt(1)
	v_sub_f32_e32 v18, v18, v17
	v_exp_f32_e32 v20, v18
	v_lshl_add_u32 v18, v21, 9, v5
	v_add_u32_e32 v21, 40, v14
	v_lshlrev_b32_e32 v22, 3, v21
	v_add3_u32 v22, 0, v22, v3
	ds_read2st64_b32 v[22:23], v22 offset0:160 offset1:162
	v_lshl_add_u32 v21, v21, 9, v5
	ds_read_b32 v18, v18
	v_pk_fma_f32 v[8:9], v[40:41], v[42:43], v[8:9] op_sel_hi:[1,0,1]
	s_waitcnt lgkmcnt(1)
	v_sub_f32_e32 v22, v22, v17
	v_exp_f32_e32 v24, v22
	ds_read_b32 v22, v21
	v_add_u32_e32 v21, 44, v14
	v_lshlrev_b32_e32 v25, 3, v21
	v_add3_u32 v25, 0, v25, v3
	ds_read2st64_b32 v[26:27], v25 offset0:160 offset1:162
	v_lshl_add_u32 v21, v21, 9, v5
	v_pk_fma_f32 v[8:9], v[10:11], v[12:13], v[8:9] op_sel_hi:[1,0,1]
	s_waitcnt lgkmcnt(0)
	v_sub_f32_e32 v25, v26, v17
	ds_read_b32 v26, v21
	v_add_u32_e32 v21, 48, v14
	v_exp_f32_e32 v28, v25
	v_lshlrev_b32_e32 v25, 3, v21
	v_add3_u32 v25, 0, v25, v3
	ds_read2st64_b32 v[30:31], v25 offset0:160 offset1:162
	v_lshl_add_u32 v21, v21, 9, v5
	s_waitcnt lgkmcnt(0)
	v_sub_f32_e32 v25, v30, v17
	ds_read_b32 v30, v21
	v_add_u32_e32 v21, 52, v14
	v_exp_f32_e32 v32, v25
	v_lshlrev_b32_e32 v25, 3, v21
	v_add3_u32 v25, 0, v25, v3
	ds_read2st64_b32 v[34:35], v25 offset0:160 offset1:162
	v_lshl_add_u32 v21, v21, 9, v5
	s_waitcnt lgkmcnt(0)
	v_sub_f32_e32 v25, v34, v17
	ds_read_b32 v34, v21
	v_add_u32_e32 v21, 56, v14
	v_exp_f32_e32 v36, v25
	v_lshlrev_b32_e32 v25, 3, v21
	v_add3_u32 v25, 0, v25, v3
	ds_read2st64_b32 v[38:39], v25 offset0:160 offset1:162
	v_lshl_add_u32 v21, v21, 9, v5
	s_waitcnt lgkmcnt(0)
	v_sub_f32_e32 v25, v38, v17
	ds_read_b32 v38, v21
	v_add_u32_e32 v21, 60, v14
	v_exp_f32_e32 v40, v25
	v_lshlrev_b32_e32 v25, 3, v21
	v_add3_u32 v25, 0, v25, v3
	ds_read2st64_b32 v[42:43], v25 offset0:160 offset1:162
	v_lshl_add_u32 v21, v21, 9, v5
	s_waitcnt lgkmcnt(0)
	v_sub_f32_e32 v25, v42, v17
	ds_read_b32 v42, v21
	v_lshl_add_u32 v21, v14, 10, v5
	ds_read_b32 v46, v21 offset:32768
	ds_read_b32 v47, v16 offset:42112
	v_lshl_or_b32 v21, v14, 1, 1
	v_lshlrev_b32_e32 v16, 3, v21
	v_add3_u32 v16, 0, v16, v3
	v_add_u32_e32 v16, 0xa400, v16
	ds_read2_b32 v[48:49], v16 offset1:32
	v_lshl_add_u32 v21, v21, 9, v5
	v_exp_f32_e32 v44, v25
	s_waitcnt lgkmcnt(0)
	v_sub_f32_e32 v16, v48, v17
	ds_read_b32 v48, v21 offset:32768
	v_lshl_add_u32 v21, v7, 10, v5
	v_lshl_or_b32 v7, v7, 1, 1
	ds_read_b32 v50, v21 offset:32768
	ds_read_b32 v51, v15 offset:42112
	v_lshlrev_b32_e32 v15, 3, v7
	v_add3_u32 v3, 0, v15, v3
	v_add_u32_e32 v3, 0xa400, v3
	v_pk_fma_f32 v[8:9], v[18:19], v[20:21], v[8:9] op_sel_hi:[1,0,1]
	ds_read2_b32 v[52:53], v3 offset1:32
	v_pk_fma_f32 v[8:9], v[22:23], v[24:25], v[8:9] op_sel_hi:[1,0,1]
	v_exp_f32_e32 v16, v16
	v_pk_fma_f32 v[8:9], v[26:27], v[28:29], v[8:9] op_sel_hi:[1,0,1]
	s_waitcnt lgkmcnt(0)
	v_sub_f32_e32 v3, v52, v17
	v_pk_fma_f32 v[8:9], v[30:31], v[32:33], v[8:9] op_sel_hi:[1,0,1]
	v_exp_f32_e32 v54, v3
	v_pk_fma_f32 v[8:9], v[34:35], v[36:37], v[8:9] op_sel_hi:[1,0,1]
	v_lshl_add_u32 v3, v7, 9, v5
	v_pk_fma_f32 v[8:9], v[38:39], v[40:41], v[8:9] op_sel_hi:[1,0,1]
	ds_read_b32 v52, v3 offset:32768
	v_pk_fma_f32 v[8:9], v[42:43], v[44:45], v[8:9] op_sel_hi:[1,0,1]
	v_or_b32_e32 v3, s38, v13
	v_pk_fma_f32 v[6:7], v[6:7], v[46:47], v[8:9] op_sel_hi:[0,1,1]
	v_pk_fma_f32 v[6:7], v[48:49], v[16:17], v[6:7] op_sel_hi:[1,0,1]
	s_nop 0
	v_pk_fma_f32 v[4:5], v[4:5], v[50:51], v[6:7] op_sel_hi:[0,1,1]
	v_add_u32_e32 v6, s34, v14
	v_ashrrev_i32_e32 v7, 31, v6
	v_lshlrev_b64 v[6:7], 11, v[6:7]
	v_lshl_or_b32 v6, v3, 1, v6
	s_waitcnt lgkmcnt(0)
	v_pk_fma_f32 v[4:5], v[52:53], v[54:55], v[4:5] op_sel_hi:[1,0,1]
	s_waitcnt vmcnt(0)
	v_lshlrev_b32_e32 v3, 16, v244
	v_div_scale_f32 v8, s[0:1], v5, v5, v4
	v_rcp_f32_e32 v9, v8
	s_nop 0
	v_fma_f32 v10, -v8, v9, 1.0
	v_fmac_f32_e32 v9, v10, v9
	v_div_scale_f32 v10, vcc, v4, v5, v4
	v_mul_f32_e32 v11, v10, v9
	v_fma_f32 v12, -v8, v11, v10
	v_fmac_f32_e32 v11, v12, v9
	v_fma_f32 v8, -v8, v11, v10
	v_div_fmas_f32 v8, v8, v9, v11
	v_div_fixup_f32 v4, v8, v5, v4
	v_mul_f32_e32 v3, v4, v3
	v_cvt_pk_bf16_f32 v3, v3, s0
	v_lshl_add_u64 v[4:5], s[36:37], 0, v[6:7]
	global_store_short v[4:5], v3, off

; #define LAS __attribute__((address_space(3)))
; DI int q_next(gu32* ctr, volatile LAS int* slot, int tid) {
;     __syncthreads();
;     if (tid == 0) *slot = (int)__hip_atomic_fetch_add(ctr, 1u, RLX_AGENT);
;     __syncthreads();
;     return *slot;
.LBB0_722:
	s_waitcnt vmcnt(0)
	s_barrier
	s_and_saveexec_b64 s[2:3], s[56:57]
	s_cbranch_execz .LBB0_726
	v_mov_b32_e32 v4, s49
	s_nop 0
	ds_write_b32 v4, v227

; DI f32x4 unpack4(v2u w) { return (f32x4){bflo(w.x), bfhi(w.x), bflo(w.y), bfhi(w.y)}; }
; DI float fexp2(float x) { return __builtin_amdgcn_exp2f(x); }
; DI void unit_sample_attn2(int u, const bf16* __restrict__ Q, const float* __restrict__ ckw, const float* __restrict__ cvw, const float* __restrict__ nkw, const float* __restrict__ nvw, const bf16* __restrict__ G, bf16* __restrict__ MIX, ...
;     ...
;     const int b = u >> 2, hq = u & 3, half = lane >> 5, hl = (lane >> 4) & 1, coff = hq * 128 + (lane & 31) * 4;
;     const float slope2 = fexp2(-(float)(hq * 2 + hl + 1)) * LOG2E;
;     const float* ck = ckw + (size_t)b * 2048 * 512 + coff; const float* cv = cvw + (size_t)b * 2048 * 512 + coff;
;     const float* nk = nkw + (size_t)b * 4 * 512 + coff;    const float* nv = nvw + (size_t)b * 4 * 512 + coff;
;     f32x4 q[4];
; #pragma unroll
;     for (int jj = 0; jj < 4; ++jj) q[jj] = unpack4(*(const v2u*)(Q + (size_t)(MP + b * 4 + jj) * 512 + coff));
;     const int j1 = wave & 3, sub = wave >> 2;
;     const f32x4 qs = (j1 == 0) ? q[0] : (j1 == 1) ? q[1] : (j1 == 2) ? q[2] : q[3];
;     float mB = NEG, lB = 0.f; f32x4 oB = (f32x4){0.f, 0.f, 0.f, 0.f};
.LBB0_732:
	v_bfe_u32 v137, v169, 4, 1
	v_lshl_or_b32 v5, s1, 1, v137
	v_add_u32_e32 v5, 1, v5
	v_cvt_f32_ubyte0_e32 v5, v5
	v_exp_f32_e64 v5, -v5
	v_lshlrev_b32_e32 v162, 2, v4
	v_xor_b32_e32 v4, 1, v1
	s_ashr_i32 s6, s0, 2
	v_mul_f32_e32 v136, 0x3fb8aa3b, v5
	v_and_b32_e32 v5, 64, v1
	v_add_u32_e32 v5, 64, v5
	v_cmp_lt_i32_e32 vcc, v4, v5
	s_ashr_i32 s7, s6, 31
	v_readlane_b32 s8, v247, 2
	v_cndmask_b32_e32 v4, v1, v4, vcc
	v_lshlrev_b32_e32 v168, 2, v4
	v_xor_b32_e32 v4, 2, v1
	v_cmp_lt_i32_e32 vcc, v4, v5
	s_lshl_b64 s[0:1], s[6:7], 22
	v_readlane_b32 s16, v247, 10
	v_cndmask_b32_e32 v4, v1, v4, vcc
	v_lshlrev_b32_e32 v167, 2, v4
	v_xor_b32_e32 v4, 4, v1
	v_cmp_lt_i32_e32 vcc, v4, v5
	v_readlane_b32 s17, v247, 11
	s_add_u32 s2, s16, s0
	v_cndmask_b32_e32 v4, v1, v4, vcc
	v_lshlrev_b32_e32 v166, 2, v4
	v_xor_b32_e32 v4, 8, v1
	v_readlane_b32 s14, v247, 8
	s_addc_u32 s3, s17, s1
	v_cmp_lt_i32_e32 vcc, v4, v5
	v_readlane_b32 s15, v247, 9
	v_ashrrev_i32_e32 v170, 5, v169
	s_add_u32 s0, s14, s0
	v_cndmask_b32_e32 v4, v1, v4, vcc
	s_addc_u32 s1, s15, s1
	v_mov_b32_e32 v163, v2
	v_lshlrev_b32_e32 v165, 2, v4
	v_lshlrev_b32_e32 v4, 2, v170
	v_lshl_add_u64 v[156:157], s[0:1], 0, v[162:163]
	v_lshl_add_u64 v[154:155], s[2:3], 0, v[162:163]
	v_sub_u32_e32 v163, 0x188, v4
	v_add_u32_e32 v171, 0xfffffe00, v4
	v_lshlrev_b32_e32 v4, 4, v170
	v_mov_b32_e32 v87, 0
	v_add_u32_e32 v172, 0x3f0, v4
	v_sub_u32_e32 v173, 0xfffffc10, v4
	v_mov_b32_e32 v85, 0xf149f2ca
	s_movk_i32 s2, 0xffe0
	v_mov_b32_e32 v4, 0
	v_mov_b32_e32 v5, v87
	v_mov_b32_e32 v6, v87
	v_mov_b32_e32 v7, v87
	v_readlane_b32 s9, v247, 3
	v_readlane_b32 s10, v247, 4
	v_readlane_b32 s11, v247, 5
	v_readlane_b32 s12, v247, 6
	v_readlane_b32 s13, v247, 7
	v_readlane_b32 s18, v247, 12
	v_readlane_b32 s19, v247, 13
	v_readlane_b32 s20, v247, 14
	v_readlane_b32 s21, v247, 15
	v_readlane_b32 s22, v247, 16
	v_readlane_b32 s23, v247, 17
	s_and_saveexec_b64 vcc, s[56:57]
	v_mov_b32_e32 v227, 1
	global_atomic_add v227, v2, v227, s[58:59] sc0
	s_mov_b64 exec, vcc
